# EpiGU straight-line path: exp/rcp interleaved with the independent packed multiplies and adds (same 44 VALU per 8 outputs)
# speedup vs baseline: 1.0017x; 1.0017x over previous
; __device__ __forceinline__ unsigned cvt_pk_bf16(float lo, float hi) { f32x2 v = {lo, hi}; return __builtin_bit_cast(unsigned, __builtin_convertvector(v, nbf16x2e)); }
;     __device__ __forceinline__ void operator()(const f32x4 (&acc)[2][2][4][2], const Unit& u, int wr, int wc, int fr, int fq) const {
;     ...
;                 const int row = row0 + ai * HALF + m * 16;
;                 float rs;
;                 if (rsc) rs = rsc[row - rbase];
;                 else {
;                     const f32x4* pp = (const f32x4*)(part + (size_t)row * 16);
;                     const f32x4 p0 = pp[0], p1 = pp[1], p2 = pp[2], p3 = pp[3];
;                     const float ssq = ((p0[0] + p0[1]) + (p0[2] + p0[3])) + ((p1[0] + p1[1]) + (p1[2] + p1[3])) + ((p2[0] + p2[1]) + (p2[2] + p2[3])) + ((p3[0] + p3[1]) + (p3[2] + p3[3]));
;                     rs = __builtin_amdgcn_rsqf(ssq * (1.0f / 1024.0f) + 1e-6f);
;                 }
;                 float v[8];
; #pragma unroll
;                 for (int n = 0; n < 2; ++n)
; #pragma unroll
;                     for (int i = 0; i < 4; ++i) { const float g = acc[ai][0][m][n][i] * rs, up = acc[ai][1][m][n][i] * rs; v[4 * n + i] = g * __builtin_amdgcn_rcpf(1.0f + __expf(-g)) * up; }
;                 u32x4 w; w.x = cvt_pk_bf16(v[0], v[1]); w.y = cvt_pk_bf16(v[2], v[3]); w.z = cvt_pk_bf16(v[4], v[5]); w.w = cvt_pk_bf16(v[6], v[7]);
;                 *(u32x4*)(O + (size_t)row * 2816 + u.pn * HALF + wc * 32 + 8 * fq) = w;
.Lgu_fast:
	s_lshl_b32 s24, s24, 7
	s_ashr_i32 s25, s24, 31
	v_mov_b64_e32 v[236:237], s[34:35]
	v_mad_u64_u32 v[236:237], s[26:27], v148, s68, v[236:237]
	v_lshl_add_u64 v[236:237], s[24:25], 1, v[236:237]
	v_lshl_add_u64 v[236:237], v[236:237], 0, s[4:5]
	v_lshl_add_u64 v[236:237], v[236:237], 0, v[138:139]
	v_pk_mul_f32 v[126:127], v[126:127], v[228:229] op_sel_hi:[1,0]
	v_pk_mul_f32 v[128:129], v[128:129], v[228:229] op_sel_hi:[1,0]
	v_pk_mul_f32 v[122:123], v[122:123], v[228:229] op_sel_hi:[1,0]
	v_pk_mul_f32 v[124:125], v[124:125], v[228:229] op_sel_hi:[1,0]
	v_pk_mul_f32 v[176:177], v[126:127], v[184:185] op_sel_hi:[1,0]
	v_pk_mul_f32 v[178:179], v[128:129], v[184:185] op_sel_hi:[1,0]
	v_pk_mul_f32 v[180:181], v[122:123], v[184:185] op_sel_hi:[1,0]
	v_pk_mul_f32 v[182:183], v[124:125], v[184:185] op_sel_hi:[1,0]
	v_exp_f32_e32 v176, v176
	v_exp_f32_e32 v177, v177
	v_exp_f32_e32 v178, v178
	v_exp_f32_e32 v179, v179
	v_pk_mul_f32 v[118:119], v[118:119], v[228:229] op_sel_hi:[1,0]
	v_pk_add_f32 v[176:177], v[176:177], v[186:187] op_sel_hi:[1,0]
	v_exp_f32_e32 v180, v180
	v_exp_f32_e32 v181, v181
	v_pk_mul_f32 v[120:121], v[120:121], v[228:229] op_sel_hi:[1,0]
	v_pk_add_f32 v[178:179], v[178:179], v[186:187] op_sel_hi:[1,0]
	v_rcp_f32_e32 v176, v176
	v_rcp_f32_e32 v177, v177
	v_exp_f32_e32 v182, v182
	v_exp_f32_e32 v183, v183
	v_pk_mul_f32 v[114:115], v[114:115], v[228:229] op_sel_hi:[1,0]
	v_pk_add_f32 v[180:181], v[180:181], v[186:187] op_sel_hi:[1,0]
	v_rcp_f32_e32 v178, v178
	v_rcp_f32_e32 v179, v179
	v_pk_mul_f32 v[116:117], v[116:117], v[228:229] op_sel_hi:[1,0]
	v_pk_add_f32 v[182:183], v[182:183], v[186:187] op_sel_hi:[1,0]
	v_pk_mul_f32 v[126:127], v[126:127], v[176:177]
	v_rcp_f32_e32 v180, v180
	v_rcp_f32_e32 v181, v181
	v_pk_mul_f32 v[128:129], v[128:129], v[178:179]
	v_rcp_f32_e32 v182, v182
	v_rcp_f32_e32 v183, v183
	v_pk_mul_f32 v[118:119], v[118:119], v[126:127]
	v_pk_mul_f32 v[122:123], v[122:123], v[180:181]
	v_pk_mul_f32 v[120:121], v[120:121], v[128:129]
	v_pk_mul_f32 v[124:125], v[124:125], v[182:183]
	v_pk_mul_f32 v[122:123], v[114:115], v[122:123]
	v_cvt_pk_bf16_f32 v114, v118, v119
	v_pk_mul_f32 v[124:125], v[116:117], v[124:125]
	v_cvt_pk_bf16_f32 v115, v120, v121
	v_cvt_pk_bf16_f32 v116, v122, v123
	v_cvt_pk_bf16_f32 v117, v124, v125
	global_store_dwordx4 v[236:237], v[114:117], off
	v_mov_b32_e32 v188, v229
	v_pk_mul_f32 v[110:111], v[110:111], v[188:189] op_sel_hi:[1,0]
	v_pk_mul_f32 v[112:113], v[112:113], v[188:189] op_sel_hi:[1,0]
	v_pk_mul_f32 v[106:107], v[106:107], v[188:189] op_sel_hi:[1,0]
	v_pk_mul_f32 v[108:109], v[108:109], v[188:189] op_sel_hi:[1,0]
	v_pk_mul_f32 v[176:177], v[110:111], v[184:185] op_sel_hi:[1,0]
	v_pk_mul_f32 v[178:179], v[112:113], v[184:185] op_sel_hi:[1,0]
	v_pk_mul_f32 v[180:181], v[106:107], v[184:185] op_sel_hi:[1,0]
	v_pk_mul_f32 v[182:183], v[108:109], v[184:185] op_sel_hi:[1,0]
	v_exp_f32_e32 v176, v176
	v_exp_f32_e32 v177, v177
	v_exp_f32_e32 v178, v178
	v_exp_f32_e32 v179, v179
	v_pk_mul_f32 v[102:103], v[102:103], v[188:189] op_sel_hi:[1,0]
	v_pk_add_f32 v[176:177], v[176:177], v[186:187] op_sel_hi:[1,0]
	v_exp_f32_e32 v180, v180
	v_exp_f32_e32 v181, v181
	v_pk_mul_f32 v[104:105], v[104:105], v[188:189] op_sel_hi:[1,0]
	v_pk_add_f32 v[178:179], v[178:179], v[186:187] op_sel_hi:[1,0]
	v_rcp_f32_e32 v176, v176
	v_rcp_f32_e32 v177, v177
	v_exp_f32_e32 v182, v182
	v_exp_f32_e32 v183, v183
	v_pk_mul_f32 v[98:99], v[98:99], v[188:189] op_sel_hi:[1,0]
	v_pk_add_f32 v[180:181], v[180:181], v[186:187] op_sel_hi:[1,0]
	v_rcp_f32_e32 v178, v178
	v_rcp_f32_e32 v179, v179
	v_pk_mul_f32 v[100:101], v[100:101], v[188:189] op_sel_hi:[1,0]
	v_pk_add_f32 v[182:183], v[182:183], v[186:187] op_sel_hi:[1,0]
	v_pk_mul_f32 v[110:111], v[110:111], v[176:177]
	v_rcp_f32_e32 v180, v180
	v_rcp_f32_e32 v181, v181
	v_pk_mul_f32 v[112:113], v[112:113], v[178:179]
	v_rcp_f32_e32 v182, v182
	v_rcp_f32_e32 v183, v183
	v_pk_mul_f32 v[102:103], v[102:103], v[110:111]
	v_pk_mul_f32 v[106:107], v[106:107], v[180:181]
	v_pk_mul_f32 v[104:105], v[104:105], v[112:113]
	v_pk_mul_f32 v[108:109], v[108:109], v[182:183]
	v_pk_mul_f32 v[106:107], v[98:99], v[106:107]
	v_cvt_pk_bf16_f32 v98, v102, v103
	v_pk_mul_f32 v[108:109], v[100:101], v[108:109]
	v_cvt_pk_bf16_f32 v99, v104, v105
	v_cvt_pk_bf16_f32 v100, v106, v107
	v_cvt_pk_bf16_f32 v101, v108, v109
	v_lshl_add_u64 v[236:237], v[236:237], 0, s[100:101]
	global_store_dwordx4 v[236:237], v[98:101], off
	v_pk_mul_f32 v[94:95], v[94:95], v[230:231] op_sel_hi:[1,0]
	v_pk_mul_f32 v[96:97], v[96:97], v[230:231] op_sel_hi:[1,0]
	v_pk_mul_f32 v[90:91], v[90:91], v[230:231] op_sel_hi:[1,0]
	v_pk_mul_f32 v[92:93], v[92:93], v[230:231] op_sel_hi:[1,0]
	v_pk_mul_f32 v[176:177], v[94:95], v[184:185] op_sel_hi:[1,0]
	v_pk_mul_f32 v[178:179], v[96:97], v[184:185] op_sel_hi:[1,0]
	v_pk_mul_f32 v[180:181], v[90:91], v[184:185] op_sel_hi:[1,0]
	v_pk_mul_f32 v[182:183], v[92:93], v[184:185] op_sel_hi:[1,0]
	v_exp_f32_e32 v176, v176
	v_exp_f32_e32 v177, v177
	v_exp_f32_e32 v178, v178
	v_exp_f32_e32 v179, v179
	v_pk_mul_f32 v[86:87], v[86:87], v[230:231] op_sel_hi:[1,0]
	v_pk_add_f32 v[176:177], v[176:177], v[186:187] op_sel_hi:[1,0]
	v_exp_f32_e32 v180, v180
	v_exp_f32_e32 v181, v181
	v_pk_mul_f32 v[88:89], v[88:89], v[230:231] op_sel_hi:[1,0]
	v_pk_add_f32 v[178:179], v[178:179], v[186:187] op_sel_hi:[1,0]
	v_rcp_f32_e32 v176, v176
	v_rcp_f32_e32 v177, v177
	v_exp_f32_e32 v182, v182
	v_exp_f32_e32 v183, v183
	v_pk_mul_f32 v[82:83], v[82:83], v[230:231] op_sel_hi:[1,0]
	v_pk_add_f32 v[180:181], v[180:181], v[186:187] op_sel_hi:[1,0]
	v_rcp_f32_e32 v178, v178
	v_rcp_f32_e32 v179, v179
; __device__ __forceinline__ unsigned cvt_pk_bf16(float lo, float hi) { f32x2 v = {lo, hi}; return __builtin_bit_cast(unsigned, __builtin_convertvector(v, nbf16x2e)); }
;     __device__ __forceinline__ void operator()(const f32x4 (&acc)[2][2][4][2], const Unit& u, int wr, int wc, int fr, int fq) const {
;     ...
;                 const int row = row0 + ai * HALF + m * 16;
;                 float rs;
;                 if (rsc) rs = rsc[row - rbase];
;                 else {
;                     const f32x4* pp = (const f32x4*)(part + (size_t)row * 16);
;                     const f32x4 p0 = pp[0], p1 = pp[1], p2 = pp[2], p3 = pp[3];
;                     const float ssq = ((p0[0] + p0[1]) + (p0[2] + p0[3])) + ((p1[0] + p1[1]) + (p1[2] + p1[3])) + ((p2[0] + p2[1]) + (p2[2] + p2[3])) + ((p3[0] + p3[1]) + (p3[2] + p3[3]));
;                     rs = __builtin_amdgcn_rsqf(ssq * (1.0f / 1024.0f) + 1e-6f);
;                 }
;                 float v[8];
; #pragma unroll
;                 for (int n = 0; n < 2; ++n)
; #pragma unroll
;                     for (int i = 0; i < 4; ++i) { const float g = acc[ai][0][m][n][i] * rs, up = acc[ai][1][m][n][i] * rs; v[4 * n + i] = g * __builtin_amdgcn_rcpf(1.0f + __expf(-g)) * up; }
;                 u32x4 w; w.x = cvt_pk_bf16(v[0], v[1]); w.y = cvt_pk_bf16(v[2], v[3]); w.z = cvt_pk_bf16(v[4], v[5]); w.w = cvt_pk_bf16(v[6], v[7]);
;                 *(u32x4*)(O + (size_t)row * 2816 + u.pn * HALF + wc * 32 + 8 * fq) = w;
	v_pk_mul_f32 v[84:85], v[84:85], v[230:231] op_sel_hi:[1,0]
	v_pk_add_f32 v[182:183], v[182:183], v[186:187] op_sel_hi:[1,0]
	v_pk_mul_f32 v[94:95], v[94:95], v[176:177]
	v_rcp_f32_e32 v180, v180
	v_rcp_f32_e32 v181, v181
	v_pk_mul_f32 v[96:97], v[96:97], v[178:179]
	v_rcp_f32_e32 v182, v182
	v_rcp_f32_e32 v183, v183
	v_pk_mul_f32 v[86:87], v[86:87], v[94:95]
	v_pk_mul_f32 v[90:91], v[90:91], v[180:181]
	v_pk_mul_f32 v[88:89], v[88:89], v[96:97]
	v_pk_mul_f32 v[92:93], v[92:93], v[182:183]
	v_pk_mul_f32 v[90:91], v[82:83], v[90:91]
	v_cvt_pk_bf16_f32 v82, v86, v87
	v_pk_mul_f32 v[92:93], v[84:85], v[92:93]
	v_cvt_pk_bf16_f32 v83, v88, v89
	v_cvt_pk_bf16_f32 v84, v90, v91
	v_cvt_pk_bf16_f32 v85, v92, v93
	v_lshl_add_u64 v[236:237], v[236:237], 0, s[100:101]
	global_store_dwordx4 v[236:237], v[82:85], off
	v_mov_b32_e32 v188, v231
	v_pk_mul_f32 v[78:79], v[78:79], v[188:189] op_sel_hi:[1,0]
	v_pk_mul_f32 v[80:81], v[80:81], v[188:189] op_sel_hi:[1,0]
	v_pk_mul_f32 v[74:75], v[74:75], v[188:189] op_sel_hi:[1,0]
	v_pk_mul_f32 v[76:77], v[76:77], v[188:189] op_sel_hi:[1,0]
	v_pk_mul_f32 v[176:177], v[78:79], v[184:185] op_sel_hi:[1,0]
	v_pk_mul_f32 v[178:179], v[80:81], v[184:185] op_sel_hi:[1,0]
	v_pk_mul_f32 v[180:181], v[74:75], v[184:185] op_sel_hi:[1,0]
	v_pk_mul_f32 v[182:183], v[76:77], v[184:185] op_sel_hi:[1,0]
	v_exp_f32_e32 v176, v176
	v_exp_f32_e32 v177, v177
	v_exp_f32_e32 v178, v178
	v_exp_f32_e32 v179, v179
	v_pk_mul_f32 v[70:71], v[70:71], v[188:189] op_sel_hi:[1,0]
	v_pk_add_f32 v[176:177], v[176:177], v[186:187] op_sel_hi:[1,0]
	v_exp_f32_e32 v180, v180
	v_exp_f32_e32 v181, v181
	v_pk_mul_f32 v[72:73], v[72:73], v[188:189] op_sel_hi:[1,0]
	v_pk_add_f32 v[178:179], v[178:179], v[186:187] op_sel_hi:[1,0]
	v_rcp_f32_e32 v176, v176
	v_rcp_f32_e32 v177, v177
	v_exp_f32_e32 v182, v182
	v_exp_f32_e32 v183, v183
	v_pk_mul_f32 v[66:67], v[66:67], v[188:189] op_sel_hi:[1,0]
	v_pk_add_f32 v[180:181], v[180:181], v[186:187] op_sel_hi:[1,0]
	v_rcp_f32_e32 v178, v178
	v_rcp_f32_e32 v179, v179
	v_pk_mul_f32 v[68:69], v[68:69], v[188:189] op_sel_hi:[1,0]
	v_pk_add_f32 v[182:183], v[182:183], v[186:187] op_sel_hi:[1,0]
	v_pk_mul_f32 v[78:79], v[78:79], v[176:177]
	v_rcp_f32_e32 v180, v180
	v_rcp_f32_e32 v181, v181
	v_pk_mul_f32 v[80:81], v[80:81], v[178:179]
	v_rcp_f32_e32 v182, v182
	v_rcp_f32_e32 v183, v183
	v_pk_mul_f32 v[70:71], v[70:71], v[78:79]
	v_pk_mul_f32 v[74:75], v[74:75], v[180:181]
	v_pk_mul_f32 v[72:73], v[72:73], v[80:81]
	v_pk_mul_f32 v[76:77], v[76:77], v[182:183]
	v_pk_mul_f32 v[74:75], v[66:67], v[74:75]
	v_cvt_pk_bf16_f32 v66, v70, v71
	v_pk_mul_f32 v[76:77], v[68:69], v[76:77]
	v_cvt_pk_bf16_f32 v67, v72, v73
	v_cvt_pk_bf16_f32 v68, v74, v75
	v_cvt_pk_bf16_f32 v69, v76, v77
	v_lshl_add_u64 v[236:237], v[236:237], 0, s[100:101]
	global_store_dwordx4 v[236:237], v[66:69], off
	v_pk_mul_f32 v[62:63], v[62:63], v[232:233] op_sel_hi:[1,0]
	v_pk_mul_f32 v[64:65], v[64:65], v[232:233] op_sel_hi:[1,0]
	v_pk_mul_f32 v[58:59], v[58:59], v[232:233] op_sel_hi:[1,0]
	v_pk_mul_f32 v[60:61], v[60:61], v[232:233] op_sel_hi:[1,0]
	v_pk_mul_f32 v[176:177], v[62:63], v[184:185] op_sel_hi:[1,0]
	v_pk_mul_f32 v[178:179], v[64:65], v[184:185] op_sel_hi:[1,0]
	v_pk_mul_f32 v[180:181], v[58:59], v[184:185] op_sel_hi:[1,0]
	v_pk_mul_f32 v[182:183], v[60:61], v[184:185] op_sel_hi:[1,0]
	v_exp_f32_e32 v176, v176
	v_exp_f32_e32 v177, v177
	v_exp_f32_e32 v178, v178
	v_exp_f32_e32 v179, v179
	v_pk_mul_f32 v[54:55], v[54:55], v[232:233] op_sel_hi:[1,0]
	v_pk_add_f32 v[176:177], v[176:177], v[186:187] op_sel_hi:[1,0]
	v_exp_f32_e32 v180, v180
	v_exp_f32_e32 v181, v181
	v_pk_mul_f32 v[56:57], v[56:57], v[232:233] op_sel_hi:[1,0]
	v_pk_add_f32 v[178:179], v[178:179], v[186:187] op_sel_hi:[1,0]
	v_rcp_f32_e32 v176, v176
	v_rcp_f32_e32 v177, v177
	v_exp_f32_e32 v182, v182
	v_exp_f32_e32 v183, v183
	v_pk_mul_f32 v[50:51], v[50:51], v[232:233] op_sel_hi:[1,0]
	v_pk_add_f32 v[180:181], v[180:181], v[186:187] op_sel_hi:[1,0]
	v_rcp_f32_e32 v178, v178
	v_rcp_f32_e32 v179, v179
	v_pk_mul_f32 v[52:53], v[52:53], v[232:233] op_sel_hi:[1,0]
	v_pk_add_f32 v[182:183], v[182:183], v[186:187] op_sel_hi:[1,0]
	v_pk_mul_f32 v[62:63], v[62:63], v[176:177]
	v_rcp_f32_e32 v180, v180
	v_rcp_f32_e32 v181, v181
	v_pk_mul_f32 v[64:65], v[64:65], v[178:179]
	v_rcp_f32_e32 v182, v182
	v_rcp_f32_e32 v183, v183
	v_pk_mul_f32 v[54:55], v[54:55], v[62:63]
	v_pk_mul_f32 v[58:59], v[58:59], v[180:181]
	v_pk_mul_f32 v[56:57], v[56:57], v[64:65]
	v_pk_mul_f32 v[60:61], v[60:61], v[182:183]
	v_pk_mul_f32 v[58:59], v[50:51], v[58:59]
	v_cvt_pk_bf16_f32 v50, v54, v55
	v_pk_mul_f32 v[60:61], v[52:53], v[60:61]
	v_cvt_pk_bf16_f32 v51, v56, v57
	v_cvt_pk_bf16_f32 v52, v58, v59
	v_cvt_pk_bf16_f32 v53, v60, v61
	v_lshl_add_u64 v[236:237], v[236:237], 0, s[98:99]
	global_store_dwordx4 v[236:237], v[50:53], off
	v_mov_b32_e32 v188, v233
	v_pk_mul_f32 v[46:47], v[46:47], v[188:189] op_sel_hi:[1,0]
	v_pk_mul_f32 v[48:49], v[48:49], v[188:189] op_sel_hi:[1,0]
	v_pk_mul_f32 v[42:43], v[42:43], v[188:189] op_sel_hi:[1,0]
	v_pk_mul_f32 v[44:45], v[44:45], v[188:189] op_sel_hi:[1,0]
	v_pk_mul_f32 v[176:177], v[46:47], v[184:185] op_sel_hi:[1,0]
	v_pk_mul_f32 v[178:179], v[48:49], v[184:185] op_sel_hi:[1,0]
	v_pk_mul_f32 v[180:181], v[42:43], v[184:185] op_sel_hi:[1,0]
	v_pk_mul_f32 v[182:183], v[44:45], v[184:185] op_sel_hi:[1,0]
	v_exp_f32_e32 v176, v176
	v_exp_f32_e32 v177, v177
	v_exp_f32_e32 v178, v178
	v_exp_f32_e32 v179, v179
; __device__ __forceinline__ unsigned cvt_pk_bf16(float lo, float hi) { f32x2 v = {lo, hi}; return __builtin_bit_cast(unsigned, __builtin_convertvector(v, nbf16x2e)); }
;     __device__ __forceinline__ void operator()(const f32x4 (&acc)[2][2][4][2], const Unit& u, int wr, int wc, int fr, int fq) const {
;     ...
;                 const int row = row0 + ai * HALF + m * 16;
;                 float rs;
;                 if (rsc) rs = rsc[row - rbase];
;                 else {
;                     const f32x4* pp = (const f32x4*)(part + (size_t)row * 16);
;                     const f32x4 p0 = pp[0], p1 = pp[1], p2 = pp[2], p3 = pp[3];
;                     const float ssq = ((p0[0] + p0[1]) + (p0[2] + p0[3])) + ((p1[0] + p1[1]) + (p1[2] + p1[3])) + ((p2[0] + p2[1]) + (p2[2] + p2[3])) + ((p3[0] + p3[1]) + (p3[2] + p3[3]));
;                     rs = __builtin_amdgcn_rsqf(ssq * (1.0f / 1024.0f) + 1e-6f);
;                 }
;                 float v[8];
; #pragma unroll
;                 for (int n = 0; n < 2; ++n)
; #pragma unroll
;                     for (int i = 0; i < 4; ++i) { const float g = acc[ai][0][m][n][i] * rs, up = acc[ai][1][m][n][i] * rs; v[4 * n + i] = g * __builtin_amdgcn_rcpf(1.0f + __expf(-g)) * up; }
;                 u32x4 w; w.x = cvt_pk_bf16(v[0], v[1]); w.y = cvt_pk_bf16(v[2], v[3]); w.z = cvt_pk_bf16(v[4], v[5]); w.w = cvt_pk_bf16(v[6], v[7]);
;                 *(u32x4*)(O + (size_t)row * 2816 + u.pn * HALF + wc * 32 + 8 * fq) = w;
	v_pk_mul_f32 v[38:39], v[38:39], v[188:189] op_sel_hi:[1,0]
	v_pk_add_f32 v[176:177], v[176:177], v[186:187] op_sel_hi:[1,0]
	v_exp_f32_e32 v180, v180
	v_exp_f32_e32 v181, v181
	v_pk_mul_f32 v[40:41], v[40:41], v[188:189] op_sel_hi:[1,0]
	v_pk_add_f32 v[178:179], v[178:179], v[186:187] op_sel_hi:[1,0]
	v_rcp_f32_e32 v176, v176
	v_rcp_f32_e32 v177, v177
	v_exp_f32_e32 v182, v182
	v_exp_f32_e32 v183, v183
	v_pk_mul_f32 v[34:35], v[34:35], v[188:189] op_sel_hi:[1,0]
	v_pk_add_f32 v[180:181], v[180:181], v[186:187] op_sel_hi:[1,0]
	v_rcp_f32_e32 v178, v178
	v_rcp_f32_e32 v179, v179
	v_pk_mul_f32 v[36:37], v[36:37], v[188:189] op_sel_hi:[1,0]
	v_pk_add_f32 v[182:183], v[182:183], v[186:187] op_sel_hi:[1,0]
	v_pk_mul_f32 v[46:47], v[46:47], v[176:177]
	v_rcp_f32_e32 v180, v180
	v_rcp_f32_e32 v181, v181
	v_pk_mul_f32 v[48:49], v[48:49], v[178:179]
	v_rcp_f32_e32 v182, v182
	v_rcp_f32_e32 v183, v183
	v_pk_mul_f32 v[38:39], v[38:39], v[46:47]
	v_pk_mul_f32 v[42:43], v[42:43], v[180:181]
	v_pk_mul_f32 v[40:41], v[40:41], v[48:49]
	v_pk_mul_f32 v[44:45], v[44:45], v[182:183]
	v_pk_mul_f32 v[42:43], v[34:35], v[42:43]
	v_cvt_pk_bf16_f32 v34, v38, v39
	v_pk_mul_f32 v[44:45], v[36:37], v[44:45]
	v_cvt_pk_bf16_f32 v35, v40, v41
	v_cvt_pk_bf16_f32 v36, v42, v43
	v_cvt_pk_bf16_f32 v37, v44, v45
	v_lshl_add_u64 v[236:237], v[236:237], 0, s[100:101]
	global_store_dwordx4 v[236:237], v[34:37], off
	v_pk_mul_f32 v[30:31], v[30:31], v[234:235] op_sel_hi:[1,0]
	v_pk_mul_f32 v[32:33], v[32:33], v[234:235] op_sel_hi:[1,0]
	v_pk_mul_f32 v[26:27], v[26:27], v[234:235] op_sel_hi:[1,0]
	v_pk_mul_f32 v[28:29], v[28:29], v[234:235] op_sel_hi:[1,0]
	v_pk_mul_f32 v[176:177], v[30:31], v[184:185] op_sel_hi:[1,0]
	v_pk_mul_f32 v[178:179], v[32:33], v[184:185] op_sel_hi:[1,0]
	v_pk_mul_f32 v[180:181], v[26:27], v[184:185] op_sel_hi:[1,0]
	v_pk_mul_f32 v[182:183], v[28:29], v[184:185] op_sel_hi:[1,0]
	v_exp_f32_e32 v176, v176
	v_exp_f32_e32 v177, v177
	v_exp_f32_e32 v178, v178
	v_exp_f32_e32 v179, v179
	v_pk_mul_f32 v[22:23], v[22:23], v[234:235] op_sel_hi:[1,0]
	v_pk_add_f32 v[176:177], v[176:177], v[186:187] op_sel_hi:[1,0]
	v_exp_f32_e32 v180, v180
	v_exp_f32_e32 v181, v181
	v_pk_mul_f32 v[24:25], v[24:25], v[234:235] op_sel_hi:[1,0]
	v_pk_add_f32 v[178:179], v[178:179], v[186:187] op_sel_hi:[1,0]
	v_rcp_f32_e32 v176, v176
	v_rcp_f32_e32 v177, v177
	v_exp_f32_e32 v182, v182
	v_exp_f32_e32 v183, v183
	v_pk_mul_f32 v[18:19], v[18:19], v[234:235] op_sel_hi:[1,0]
	v_pk_add_f32 v[180:181], v[180:181], v[186:187] op_sel_hi:[1,0]
	v_rcp_f32_e32 v178, v178
	v_rcp_f32_e32 v179, v179
	v_pk_mul_f32 v[20:21], v[20:21], v[234:235] op_sel_hi:[1,0]
	v_pk_add_f32 v[182:183], v[182:183], v[186:187] op_sel_hi:[1,0]
	v_pk_mul_f32 v[30:31], v[30:31], v[176:177]
	v_rcp_f32_e32 v180, v180
	v_rcp_f32_e32 v181, v181
	v_pk_mul_f32 v[32:33], v[32:33], v[178:179]
	v_rcp_f32_e32 v182, v182
	v_rcp_f32_e32 v183, v183
	v_pk_mul_f32 v[22:23], v[22:23], v[30:31]
	v_pk_mul_f32 v[26:27], v[26:27], v[180:181]
	v_pk_mul_f32 v[24:25], v[24:25], v[32:33]
	v_pk_mul_f32 v[28:29], v[28:29], v[182:183]
	v_pk_mul_f32 v[26:27], v[18:19], v[26:27]
	v_cvt_pk_bf16_f32 v18, v22, v23
	v_pk_mul_f32 v[28:29], v[20:21], v[28:29]
	v_cvt_pk_bf16_f32 v19, v24, v25
	v_cvt_pk_bf16_f32 v20, v26, v27
	v_cvt_pk_bf16_f32 v21, v28, v29
	v_lshl_add_u64 v[236:237], v[236:237], 0, s[100:101]
	global_store_dwordx4 v[236:237], v[18:21], off
	v_mov_b32_e32 v188, v235
	v_pk_mul_f32 v[14:15], v[14:15], v[188:189] op_sel_hi:[1,0]
	v_pk_mul_f32 v[16:17], v[16:17], v[188:189] op_sel_hi:[1,0]
	v_pk_mul_f32 v[10:11], v[10:11], v[188:189] op_sel_hi:[1,0]
	v_pk_mul_f32 v[12:13], v[12:13], v[188:189] op_sel_hi:[1,0]
	v_pk_mul_f32 v[176:177], v[14:15], v[184:185] op_sel_hi:[1,0]
	v_pk_mul_f32 v[178:179], v[16:17], v[184:185] op_sel_hi:[1,0]
	v_pk_mul_f32 v[180:181], v[10:11], v[184:185] op_sel_hi:[1,0]
	v_pk_mul_f32 v[182:183], v[12:13], v[184:185] op_sel_hi:[1,0]
	v_exp_f32_e32 v176, v176
	v_exp_f32_e32 v177, v177
	v_exp_f32_e32 v178, v178
	v_exp_f32_e32 v179, v179
	v_pk_mul_f32 v[6:7], v[6:7], v[188:189] op_sel_hi:[1,0]
	v_pk_add_f32 v[176:177], v[176:177], v[186:187] op_sel_hi:[1,0]
	v_exp_f32_e32 v180, v180
	v_exp_f32_e32 v181, v181
	v_pk_mul_f32 v[8:9], v[8:9], v[188:189] op_sel_hi:[1,0]
	v_pk_add_f32 v[178:179], v[178:179], v[186:187] op_sel_hi:[1,0]
	v_rcp_f32_e32 v176, v176
	v_rcp_f32_e32 v177, v177
	v_exp_f32_e32 v182, v182
	v_exp_f32_e32 v183, v183
	v_pk_mul_f32 v[2:3], v[2:3], v[188:189] op_sel_hi:[1,0]
	v_pk_add_f32 v[180:181], v[180:181], v[186:187] op_sel_hi:[1,0]
	v_rcp_f32_e32 v178, v178
	v_rcp_f32_e32 v179, v179
	v_pk_mul_f32 v[4:5], v[4:5], v[188:189] op_sel_hi:[1,0]
	v_pk_add_f32 v[182:183], v[182:183], v[186:187] op_sel_hi:[1,0]
	v_pk_mul_f32 v[14:15], v[14:15], v[176:177]
	v_rcp_f32_e32 v180, v180
	v_rcp_f32_e32 v181, v181
	v_pk_mul_f32 v[16:17], v[16:17], v[178:179]
	v_rcp_f32_e32 v182, v182
	v_rcp_f32_e32 v183, v183
	v_pk_mul_f32 v[6:7], v[6:7], v[14:15]
	v_pk_mul_f32 v[10:11], v[10:11], v[180:181]
	v_pk_mul_f32 v[8:9], v[8:9], v[16:17]
	v_pk_mul_f32 v[12:13], v[12:13], v[182:183]
	v_pk_mul_f32 v[10:11], v[2:3], v[10:11]
	v_cvt_pk_bf16_f32 v2, v6, v7
	v_pk_mul_f32 v[12:13], v[4:5], v[12:13]
	v_cvt_pk_bf16_f32 v3, v8, v9
	v_cvt_pk_bf16_f32 v4, v10, v11
	v_cvt_pk_bf16_f32 v5, v12, v13
	v_lshl_add_u64 v[236:237], v[236:237], 0, s[100:101]
	s_andn2_b64 vcc, exec, s[0:1]
	s_mov_b64 s[0:1], -1
	global_store_dwordx4 v[236:237], v[2:5], off
	s_branch .Lgu_done
